# mini_ring loop: address VALU hoisted above chunk barrier, DMA m0 save/restore dropped; hgrn_pass2 S_in correction MFMAs with 12-deep LDS reads and counted lgkmcnt
# baseline (speedup 1.0000x reference)
; __device__ __forceinline__ float bf_lo(unsigned w) { return __uint_as_float(w << 16); }
; __device__ __forceinline__ float bf_hi(unsigned w) { return __uint_as_float(w & 0xffff0000u); }
; #define LAS __attribute__((address_space(3)))
; __device__ __forceinline__ f32x4 mfma16(bf16x8 a, bf16x8 b, f32x4 c) { return __builtin_amdgcn_mfma_f32_16x16x32_bf16(a, b, c, 0, 0, 0); }
; __device__ __forceinline__ void hgrn_pass2(const Frame& F, unsigned char* ws, const float* gw, float* o_state  ) {
;     ...
;         for (int u2 = 0; u2 < 2; ++u2) { const int idx = 2 * w + u2, row = row_base + (idx >> 2) * 64 + 16 * (idx & 3) + li;
;             const bf16* prow = PB + (size_t)row * 2560 + h * 128;
;             f32x4 o[8]; v2u gpre[8];
; #pragma unroll
;             for (int vt = 0; vt < 8; ++vt) gpre[vt] = *(const v2u*)(prow + 1536 + 16 * vt + 4 * lq);
; #pragma unroll
;             for (int vt = 0; vt < 8; ++vt) { const v2u raw = *(const v2u*)(prow + 1024 + 16 * vt + 4 * lq); o[vt] = (f32x4){pg8::bf_lo(raw.x), pg8::bf_hi(raw.x), pg8::bf_lo(raw.y), pg8::bf_hi(raw.y)}; }
;             if (seg > 0) { bf16x8 qf[4];
; #pragma unroll
;                 for (int ks = 0; ks < 4; ++ks) qf[ks] = *(const bf16x8*)(prow + 32 * ks + 8 * lq);
; #pragma unroll
;                 for (int vt = 0; vt < 8; ++vt)
; #pragma unroll
;                     for (int ks = 0; ks < 4; ++ks) o[vt] = mfma16(*(const LAS bf16x8*)(L + (16 * vt + li) * LDQ + (32 * ks + 8 * lq) * 2), qf[ks], o[vt]); }
.LBB0_824:
	v_or_b32_e32 v148, s2, v150
	v_mov_b64_e32 v[42:43], s[14:15]
	v_mad_i64_i32 v[74:75], s[0:1], v148, s97, v[42:43]
	v_lshl_add_u64 v[42:43], v[74:75], 0, v[0:1]
	global_load_dwordx2 v[44:45], v[42:43], off offset:2048
	global_load_dwordx2 v[46:47], v[42:43], off offset:2080
	global_load_dwordx2 v[48:49], v[42:43], off offset:2112
	global_load_dwordx2 v[50:51], v[42:43], off offset:2144
	global_load_dwordx2 v[52:53], v[42:43], off offset:2176
	global_load_dwordx2 v[68:69], v[42:43], off offset:2208
	global_load_dwordx2 v[76:77], v[42:43], off offset:2240
	global_load_dwordx2 v[146:147], v[42:43], off offset:3072
	global_load_dwordx2 v[144:145], v[42:43], off offset:3104
	global_load_dwordx2 v[142:143], v[42:43], off offset:3136
	global_load_dwordx2 v[140:141], v[42:43], off offset:3168
	global_load_dwordx2 v[78:79], v[42:43], off offset:2272
	global_load_dwordx2 v[138:139], v[42:43], off offset:3200
	global_load_dwordx2 v[136:137], v[42:43], off offset:3232
	global_load_dwordx2 v[134:135], v[42:43], off offset:3264
	global_load_dwordx2 v[132:133], v[42:43], off offset:3296
	s_and_b64 vcc, exec, s[10:11]
	s_waitcnt vmcnt(15)
	v_lshlrev_b32_e32 v70, 16, v44
	v_and_b32_e32 v71, 0xffff0000, v44
	v_lshlrev_b32_e32 v72, 16, v45
	v_and_b32_e32 v73, 0xffff0000, v45
	s_waitcnt vmcnt(14)
	v_lshlrev_b32_e32 v62, 16, v46
	v_and_b32_e32 v63, 0xffff0000, v46
	v_lshlrev_b32_e32 v64, 16, v47
	v_and_b32_e32 v65, 0xffff0000, v47
	s_waitcnt vmcnt(13)
	v_lshlrev_b32_e32 v58, 16, v48
	v_and_b32_e32 v59, 0xffff0000, v48
	v_lshlrev_b32_e32 v60, 16, v49
	v_and_b32_e32 v61, 0xffff0000, v49
	s_waitcnt vmcnt(12)
	v_lshlrev_b32_e32 v54, 16, v50
	v_and_b32_e32 v55, 0xffff0000, v50
	v_lshlrev_b32_e32 v56, 16, v51
	v_and_b32_e32 v57, 0xffff0000, v51
	s_waitcnt vmcnt(11)
	v_lshlrev_b32_e32 v50, 16, v52
	v_and_b32_e32 v51, 0xffff0000, v52
	v_lshlrev_b32_e32 v52, 16, v53
	v_and_b32_e32 v53, 0xffff0000, v53
	s_waitcnt vmcnt(10)
	v_lshlrev_b32_e32 v66, 16, v68
	v_and_b32_e32 v67, 0xffff0000, v68
	v_lshlrev_b32_e32 v68, 16, v69
	v_and_b32_e32 v69, 0xffff0000, v69
	s_waitcnt vmcnt(9)
	v_lshlrev_b32_e32 v46, 16, v76
	v_and_b32_e32 v47, 0xffff0000, v76
	v_lshlrev_b32_e32 v48, 16, v77
	v_and_b32_e32 v49, 0xffff0000, v77
	s_waitcnt vmcnt(4)
	v_lshlrev_b32_e32 v42, 16, v78
	v_and_b32_e32 v43, 0xffff0000, v78
	v_lshlrev_b32_e32 v44, 16, v79
	v_and_b32_e32 v45, 0xffff0000, v79
	s_cbranch_vccnz .LBB0_823
	v_mov_b32_e32 v129, v1
	v_lshl_add_u64 v[74:75], v[74:75], 0, v[128:129]
	global_load_dwordx4 v[86:89], v[74:75], off
	global_load_dwordx4 v[82:85], v[74:75], off offset:64
	global_load_dwordx4 v[78:81], v[74:75], off offset:128
	s_nop 0
	global_load_dwordx4 v[74:77], v[74:75], off offset:192
	ds_read_b128 v[168:171], v97
	ds_read_b128 v[172:175], v97 offset:64
	ds_read_b128 v[176:179], v97 offset:128
	ds_read_b128 v[180:183], v97 offset:192
	ds_read_b128 v[184:187], v97 offset:4352
	ds_read_b128 v[188:191], v97 offset:4416
	ds_read_b128 v[200:203], v97 offset:4480
	ds_read_b128 v[204:207], v97 offset:4544
	ds_read_b128 v[208:211], v97 offset:8704
	ds_read_b128 v[224:227], v97 offset:8768
	ds_read_b128 v[228:231], v97 offset:8832
	ds_read_b128 v[232:235], v97 offset:8896
	s_waitcnt vmcnt(3) lgkmcnt(11)
	v_mfma_f32_16x16x32_bf16 v[70:73], v[168:171], v[86:89], v[70:73]
	s_waitcnt vmcnt(2) lgkmcnt(10)
	v_mfma_f32_16x16x32_bf16 v[70:73], v[172:175], v[82:85], v[70:73]
	s_waitcnt vmcnt(1) lgkmcnt(9)
	v_mfma_f32_16x16x32_bf16 v[70:73], v[176:179], v[78:81], v[70:73]
	s_waitcnt vmcnt(0) lgkmcnt(8)
	v_mfma_f32_16x16x32_bf16 v[70:73], v[180:183], v[74:77], v[70:73]
	ds_read_b128 v[168:171], v97 offset:13056
	ds_read_b128 v[172:175], v97 offset:13120
	ds_read_b128 v[176:179], v97 offset:13184
	ds_read_b128 v[180:183], v97 offset:13248
	s_waitcnt lgkmcnt(11)
	v_mfma_f32_16x16x32_bf16 v[62:65], v[184:187], v[86:89], v[62:65]
	s_waitcnt lgkmcnt(10)
	v_mfma_f32_16x16x32_bf16 v[62:65], v[188:191], v[82:85], v[62:65]
	s_waitcnt lgkmcnt(9)
	v_mfma_f32_16x16x32_bf16 v[62:65], v[200:203], v[78:81], v[62:65]
	s_waitcnt lgkmcnt(8)
	v_mfma_f32_16x16x32_bf16 v[62:65], v[204:207], v[74:77], v[62:65]
	ds_read_b128 v[184:187], v97 offset:17408
	ds_read_b128 v[188:191], v97 offset:17472
	ds_read_b128 v[200:203], v97 offset:17536
	ds_read_b128 v[204:207], v97 offset:17600
	s_waitcnt lgkmcnt(11)
	v_mfma_f32_16x16x32_bf16 v[58:61], v[208:211], v[86:89], v[58:61]
	s_waitcnt lgkmcnt(10)
	v_mfma_f32_16x16x32_bf16 v[58:61], v[224:227], v[82:85], v[58:61]
	s_waitcnt lgkmcnt(9)
	v_mfma_f32_16x16x32_bf16 v[58:61], v[228:231], v[78:81], v[58:61]
	s_waitcnt lgkmcnt(8)
	v_mfma_f32_16x16x32_bf16 v[58:61], v[232:235], v[74:77], v[58:61]
	ds_read_b128 v[208:211], v97 offset:21760
	ds_read_b128 v[224:227], v97 offset:21824
	ds_read_b128 v[228:231], v97 offset:21888
	ds_read_b128 v[232:235], v97 offset:21952
	s_waitcnt lgkmcnt(11)
	v_mfma_f32_16x16x32_bf16 v[54:57], v[168:171], v[86:89], v[54:57]
	s_waitcnt lgkmcnt(10)
	v_mfma_f32_16x16x32_bf16 v[54:57], v[172:175], v[82:85], v[54:57]
	s_waitcnt lgkmcnt(9)
	v_mfma_f32_16x16x32_bf16 v[54:57], v[176:179], v[78:81], v[54:57]
	s_waitcnt lgkmcnt(8)
	v_mfma_f32_16x16x32_bf16 v[54:57], v[180:183], v[74:77], v[54:57]
	ds_read_b128 v[168:171], v97 offset:26112
	ds_read_b128 v[172:175], v97 offset:26176
	ds_read_b128 v[176:179], v97 offset:26240
	ds_read_b128 v[180:183], v97 offset:26304
	s_waitcnt lgkmcnt(11)
	v_mfma_f32_16x16x32_bf16 v[50:53], v[184:187], v[86:89], v[50:53]
	s_waitcnt lgkmcnt(10)
	v_mfma_f32_16x16x32_bf16 v[50:53], v[188:191], v[82:85], v[50:53]
	s_waitcnt lgkmcnt(9)
	v_mfma_f32_16x16x32_bf16 v[50:53], v[200:203], v[78:81], v[50:53]
	s_waitcnt lgkmcnt(8)
	v_mfma_f32_16x16x32_bf16 v[50:53], v[204:207], v[74:77], v[50:53]
	ds_read_b128 v[184:187], v97 offset:30464
	ds_read_b128 v[188:191], v97 offset:30528
	ds_read_b128 v[200:203], v97 offset:30592
	ds_read_b128 v[204:207], v97 offset:30656
	s_waitcnt lgkmcnt(11)
	v_mfma_f32_16x16x32_bf16 v[66:69], v[208:211], v[86:89], v[66:69]
	s_waitcnt lgkmcnt(10)
	v_mfma_f32_16x16x32_bf16 v[66:69], v[224:227], v[82:85], v[66:69]
	s_waitcnt lgkmcnt(9)
	v_mfma_f32_16x16x32_bf16 v[66:69], v[228:231], v[78:81], v[66:69]
	s_waitcnt lgkmcnt(8)
	v_mfma_f32_16x16x32_bf16 v[66:69], v[232:235], v[74:77], v[66:69]
	s_waitcnt lgkmcnt(7)
	v_mfma_f32_16x16x32_bf16 v[46:49], v[168:171], v[86:89], v[46:49]
	s_waitcnt lgkmcnt(6)
	v_mfma_f32_16x16x32_bf16 v[46:49], v[172:175], v[82:85], v[46:49]
	s_waitcnt lgkmcnt(5)
	v_mfma_f32_16x16x32_bf16 v[46:49], v[176:179], v[78:81], v[46:49]
	s_waitcnt lgkmcnt(4)
	v_mfma_f32_16x16x32_bf16 v[46:49], v[180:183], v[74:77], v[46:49]
	s_waitcnt lgkmcnt(3)
	v_mfma_f32_16x16x32_bf16 v[42:45], v[184:187], v[86:89], v[42:45]
	s_waitcnt lgkmcnt(2)
	v_mfma_f32_16x16x32_bf16 v[42:45], v[188:191], v[82:85], v[42:45]
	s_waitcnt lgkmcnt(1)
	v_mfma_f32_16x16x32_bf16 v[42:45], v[200:203], v[78:81], v[42:45]
	s_waitcnt lgkmcnt(0)
	v_mfma_f32_16x16x32_bf16 v[42:45], v[204:207], v[74:77], v[42:45]
	s_branch .LBB0_823
